# v9: v8 + same load reordering/counted waits in the prompt-chain scan loop
# baseline (speedup 1.0000x reference)
.LBB0_812:
	s_ashr_i32 s5, s18, 3
	s_or_b32 s10, s5, s15
	s_ashr_i32 s11, s10, 31
	s_lshl_b64 s[10:11], s[10:11], 7
	v_lshl_add_u64 v[72:73], v[148:149], 0, s[10:11]
	v_lshlrev_b64 v[72:73], 7, v[72:73]
	v_lshl_add_u64 v[76:77], v[150:151], 0, v[72:73]
	v_lshl_add_u64 v[72:73], v[132:133], 0, s[10:11]
	v_lshlrev_b64 v[72:73], 7, v[72:73]
	v_lshl_add_u64 v[78:79], v[152:153], 0, v[72:73]
	global_load_dwordx4 v[116:119], v[76:77], off
	global_load_dwordx4 v[80:83], v[78:79], off
	global_load_dwordx4 v[72:75], v[78:79], off offset:2048
	global_load_dwordx4 v[112:115], v[76:77], off offset:64
	global_load_dwordx4 v[84:87], v[78:79], off offset:64
	s_nop 0
	global_load_dwordx4 v[76:79], v[78:79], off offset:2112
	s_min_i32 s5, s14, 3
	s_xor_b32 s20, s5, 3
	s_and_b64 s[10:11], s[0:1], exec
	s_cselect_b32 s5, s5, s20
	s_or_b32 s5, s5, s17
	s_lshl_b32 s20, s5, 6
	s_lshl_b32 s5, s5, 3
	s_or_b32 s10, s5, s15
	s_ashr_i32 s11, s10, 31
	s_lshl_b64 s[10:11], s[10:11], 1
	s_or_b64 s[10:11], s[10:11], s[6:7]
	s_lshl_b64 s[22:23], s[10:11], 14
	s_waitcnt vmcnt(22)
	v_lshl_add_u64 v[56:57], v[166:167], 0, s[22:23]
	v_add_u32_e32 v36, s20, v201
	s_lshl_b64 s[22:23], s[10:11], 7
	v_ashrrev_i32_e32 v37, 31, v36
	v_lshl_add_u64 v[64:65], s[22:23], 0, v[128:129]
	v_lshlrev_b64 v[36:37], 11, v[36:37]
	v_lshlrev_b64 v[64:65], 7, v[64:65]
	v_lshl_add_u64 v[60:61], v[168:169], 0, v[36:37]
	v_lshl_add_u64 v[64:65], v[136:137], 0, v[64:65]
	global_load_dwordx4 v[32:35], v[56:57], off
	global_load_dwordx4 v[36:39], v[60:61], off
	global_load_dwordx4 v[40:43], v[56:57], off offset:64
	global_load_dwordx4 v[44:47], v[60:61], off offset:64
	global_load_dwordx4 v[52:55], v[56:57], off offset:128
	global_load_dwordx4 v[48:51], v[60:61], off offset:128
	s_nop 0
	global_load_dwordx4 v[56:59], v[56:57], off offset:192
	s_nop 0
	global_load_dwordx4 v[60:63], v[60:61], off offset:192
	s_lshl_b64 s[10:11], s[10:11], 8
	global_load_dwordx2 v[170:171], v[64:65], off
	v_lshl_add_u64 v[64:65], v[138:139], 0, s[22:23]
	v_lshlrev_b64 v[64:65], 7, v[64:65]
	v_lshl_add_u64 v[64:65], v[136:137], 0, v[64:65]
	global_load_dwordx2 v[172:173], v[64:65], off
	v_lshl_add_u64 v[64:65], v[140:141], 0, s[22:23]
	v_lshlrev_b64 v[64:65], 7, v[64:65]
	v_lshl_add_u64 v[64:65], v[136:137], 0, v[64:65]
	global_load_dwordx2 v[174:175], v[64:65], off
	v_lshl_add_u64 v[64:65], v[142:143], 0, s[22:23]
	v_lshlrev_b64 v[64:65], 7, v[64:65]
	s_add_u32 s10, s37, s10
	v_lshl_add_u64 v[64:65], v[136:137], 0, v[64:65]
	s_addc_u32 s11, s77, s11
	global_load_dwordx2 v[176:177], v[64:65], off
	v_lshl_add_u64 v[64:65], v[134:135], 2, s[10:11]
	global_load_dwordx4 v[64:67], v[64:65], off
	s_nop 0
	global_load_dword v159, v129, s[10:11] offset:252
	s_waitcnt lgkmcnt(0)
	s_barrier
	s_cmp_eq_u32 s14, 1
	s_cbranch_scc1 .LBB0_814
	s_ashr_i32 s5, s4, 31
	s_add_u32 s4, s19, s4
	s_addc_u32 s5, 0, s5
	v_lshl_add_u64 v[186:187], s[4:5], 0, v[156:157]
	v_lshlrev_b64 v[186:187], 11, v[186:187]
	v_lshl_add_u64 v[190:191], v[146:147], 0, v[186:187]
	ds_read_b128 v[186:189], v203
	s_waitcnt lgkmcnt(0)
	global_store_dwordx4 v[190:191], v[186:189], off
	s_nop 1
	v_lshl_add_u64 v[186:187], s[4:5], 0, v[154:155]
	v_lshlrev_b64 v[186:187], 11, v[186:187]
	v_lshl_add_u64 v[190:191], v[146:147], 0, v[186:187]
	ds_read_b128 v[186:189], v202
	s_waitcnt lgkmcnt(0)
	global_store_dwordx4 v[190:191], v[186:189], off

.LBB0_830:
	v_mul_f32_e32 v68, 0x3fb8aa3b, v68
	v_exp_f32_e32 v190, v68
	v_mul_f32_e32 v68, 0x3fb8aa3b, v69
	v_exp_f32_e32 v191, v68
	v_mul_f32_e32 v68, 0x3fb8aa3b, v70
	v_exp_f32_e32 v244, v68
	v_mul_f32_e32 v68, 0x3fb8aa3b, v71
	v_exp_f32_e32 v245, v68
	s_waitcnt lgkmcnt(0)
	s_barrier
	v_pk_mul_f32 v[92:93], v[190:191], v[104:105]
	ds_read_b128 v[68:71], v213 offset:17408
	ds_read_b128 v[124:127], v213 offset:17472
	ds_read_b128 v[178:181], v213 offset:19712
	ds_read_b128 v[182:185], v213 offset:19776
	ds_read_b128 v[186:189], v213 offset:22016
	ds_read_b128 v[216:219], v213 offset:22080
	ds_read_b128 v[220:223], v213 offset:24320
	ds_read_b128 v[224:227], v213 offset:24384
	ds_read_b128 v[228:231], v213 offset:26624
	ds_read_b128 v[232:235], v213 offset:26688
	ds_read_b128 v[236:239], v213 offset:28928
	ds_read_b128 v[240:243], v213 offset:28992
	ds_read_b128 v[120:123], v213 offset:31232
	ds_read_b128 v[108:111], v213 offset:31296
	v_pk_mul_f32 v[94:95], v[244:245], v[106:107]
	v_pk_mul_f32 v[102:103], v[244:245], v[102:103]
	v_pk_mul_f32 v[100:101], v[190:191], v[100:101]
	s_waitcnt vmcnt(19) lgkmcnt(13)
	v_mfma_f32_16x16x32_bf16 v[104:107], v[116:119], v[68:71], v[92:95]
	s_nop 2
	ds_read_b128 v[92:95], v213 offset:33536
	ds_read_b128 v[68:71], v213 offset:33600
	v_pk_mul_f32 v[98:99], v[244:245], v[98:99]
	s_waitcnt vmcnt(16) lgkmcnt(14)
	v_mfma_f32_16x16x32_bf16 v[104:107], v[112:115], v[124:127], v[104:107]
	v_mul_f32_e64 v96, v190, v96
	v_mul_f32_e64 v97, v191, v97
	v_pk_mul_f32 v[90:91], v[244:245], v[90:91]
	v_pk_mul_f32 v[88:89], v[190:191], v[88:89]
	s_waitcnt lgkmcnt(13)
	v_mfma_f32_16x16x32_bf16 v[100:103], v[116:119], v[178:181], v[100:103]
	s_add_i32 s14, s14, 1
	s_nop 0
	v_bfe_u32 v124, v104, 16, 1
	v_add3_u32 v104, v104, v124, s12
	ds_write_b16_d16_hi v158, v104 offset:35840
	v_bfe_u32 v104, v105, 16, 1
	v_add3_u32 v104, v105, v104, s12
	ds_write_b16_d16_hi v160, v104 offset:35840
	v_bfe_u32 v104, v106, 16, 1
	s_waitcnt lgkmcnt(14)
	v_mfma_f32_16x16x32_bf16 v[100:103], v[112:115], v[182:185], v[100:103]
	v_add3_u32 v104, v106, v104, s12
	ds_write_b16_d16_hi v162, v104 offset:35840
	v_bfe_u32 v104, v107, 16, 1
	v_add3_u32 v104, v107, v104, s12
	ds_write_b16_d16_hi v164, v104 offset:35840
	s_nop 2
	v_bfe_u32 v104, v100, 16, 1
	s_waitcnt lgkmcnt(14)
	v_mfma_f32_16x16x32_bf16 v[96:99], v[116:119], v[186:189], v[96:99]
	v_add3_u32 v100, v100, v104, s12
	ds_write_b16_d16_hi v158, v100 offset:35872
	v_bfe_u32 v100, v101, 16, 1
	v_add3_u32 v100, v101, v100, s12
	ds_write_b16_d16_hi v160, v100 offset:35872
	v_bfe_u32 v100, v102, 16, 1
	v_mfma_f32_16x16x32_bf16 v[96:99], v[112:115], v[216:219], v[96:99]
	v_add3_u32 v100, v102, v100, s12
	ds_write_b16_d16_hi v162, v100 offset:35872
	v_bfe_u32 v100, v103, 16, 1
	v_add3_u32 v100, v103, v100, s12
	ds_write_b16_d16_hi v164, v100 offset:35872
	s_nop 2
	v_bfe_u32 v100, v96, 16, 1
	v_add3_u32 v96, v96, v100, s12
	ds_write_b16_d16_hi v158, v96 offset:35904
	v_bfe_u32 v96, v97, 16, 1
	v_add3_u32 v96, v97, v96, s12
	s_waitcnt lgkmcnt(14)
	v_mfma_f32_16x16x32_bf16 v[88:91], v[116:119], v[220:223], v[88:91]
	ds_write_b16_d16_hi v160, v96 offset:35904
	v_bfe_u32 v96, v98, 16, 1
	v_add3_u32 v97, v98, v96, s12
	v_mul_f32_e32 v96, 0x3fb8aa3b, v214
	v_exp_f32_e32 v96, v96
	v_mfma_f32_16x16x32_bf16 v[88:91], v[112:115], v[224:227], v[88:91]
	ds_write_b16_d16_hi v162, v97 offset:35904
	v_bfe_u32 v97, v99, 16, 1
	v_pk_mul_f32 v[18:19], v[18:19], v[96:97] op_sel_hi:[1,0]
	v_pk_mul_f32 v[16:17], v[16:17], v[96:97] op_sel_hi:[1,0]
	v_add3_u32 v97, v99, v97, s12
	ds_write_b16_d16_hi v164, v97 offset:35904
	s_nop 1
	v_bfe_u32 v97, v88, 16, 1
	v_pk_mul_f32 v[2:3], v[2:3], v[96:97] op_sel_hi:[1,0]
	v_pk_mul_f32 v[0:1], v[0:1], v[96:97] op_sel_hi:[1,0]
	v_mfma_f32_16x16x32_bf16 v[16:19], v[80:83], v[228:231], v[16:19]
	v_mul_f32_e64 v22, v22, v96
	v_mul_f32_e64 v23, v23, v96
	v_pk_mul_f32 v[20:21], v[20:21], v[96:97] op_sel_hi:[1,0]
	v_pk_mul_f32 v[26:27], v[26:27], v[96:97] op_sel_hi:[1,0]
	v_pk_mul_f32 v[24:25], v[24:25], v[96:97] op_sel_hi:[1,0]
	v_pk_mul_f32 v[30:31], v[30:31], v[96:97] op_sel_hi:[1,0]
	v_pk_mul_f32 v[28:29], v[28:29], v[96:97] op_sel_hi:[1,0]
	v_mfma_f32_16x16x32_bf16 v[0:3], v[72:75], v[228:231], v[0:3]
	v_mul_f32_e64 v6, v6, v96
	v_mul_f32_e64 v7, v7, v96
	v_pk_mul_f32 v[4:5], v[4:5], v[96:97] op_sel_hi:[1,0]
	v_pk_mul_f32 v[10:11], v[10:11], v[96:97] op_sel_hi:[1,0]
	v_pk_mul_f32 v[8:9], v[8:9], v[96:97] op_sel_hi:[1,0]
	v_pk_mul_f32 v[14:15], v[14:15], v[96:97] op_sel_hi:[1,0]
	v_pk_mul_f32 v[12:13], v[12:13], v[96:97] op_sel_hi:[1,0]
	v_add3_u32 v88, v88, v97, s12
	v_mfma_f32_16x16x32_bf16 v[20:23], v[80:83], v[236:239], v[20:23]
	ds_write_b16_d16_hi v158, v88 offset:35936
	v_bfe_u32 v88, v89, 16, 1
	v_add3_u32 v88, v89, v88, s12
	s_waitcnt lgkmcnt(14)
	v_mfma_f32_16x16x32_bf16 v[24:27], v[80:83], v[120:123], v[24:27]
	ds_write_b16_d16_hi v160, v88 offset:35936
	v_bfe_u32 v88, v90, 16, 1
	v_add3_u32 v88, v90, v88, s12
	v_mfma_f32_16x16x32_bf16 v[28:31], v[80:83], v[92:95], v[28:31]
	ds_write_b16_d16_hi v162, v88 offset:35936
	v_bfe_u32 v88, v91, 16, 1
	v_add3_u32 v80, v91, v88, s12
	v_mfma_f32_16x16x32_bf16 v[4:7], v[72:75], v[236:239], v[4:7]
	ds_write_b16_d16_hi v164, v80 offset:35936
	s_cmp_lg_u32 s14, 5
	v_mfma_f32_16x16x32_bf16 v[8:11], v[72:75], v[120:123], v[8:11]
	v_mfma_f32_16x16x32_bf16 v[12:15], v[72:75], v[92:95], v[12:15]
	s_waitcnt vmcnt(15)
	v_mfma_f32_16x16x32_bf16 v[16:19], v[84:87], v[232:235], v[16:19]
	s_waitcnt vmcnt(14)
	v_mfma_f32_16x16x32_bf16 v[0:3], v[76:79], v[232:235], v[0:3]
	v_mfma_f32_16x16x32_bf16 v[20:23], v[84:87], v[240:243], v[20:23]
	s_nop 4
	v_cvt_pk_bf16_f32 v81, v18, v19
	v_cvt_pk_bf16_f32 v80, v16, v17
	v_cvt_pk_bf16_f32 v89, v2, v3
	v_mfma_f32_16x16x32_bf16 v[24:27], v[84:87], v[108:111], v[24:27]
	v_cvt_pk_bf16_f32 v88, v0, v1
	v_cvt_pk_bf16_f32 v83, v22, v23
	v_cvt_pk_bf16_f32 v82, v20, v21
	s_waitcnt lgkmcnt(14)
	v_mfma_f32_16x16x32_bf16 v[28:31], v[84:87], v[68:71], v[28:31]
	ds_write2_b64 v197, v[80:81], v[88:89] offset1:4
	s_nop 1
	v_cvt_pk_bf16_f32 v85, v26, v27
	v_cvt_pk_bf16_f32 v84, v24, v25
	v_mfma_f32_16x16x32_bf16 v[4:7], v[76:79], v[240:243], v[4:7]
	v_mfma_f32_16x16x32_bf16 v[8:11], v[76:79], v[108:111], v[8:11]
	s_nop 0
	v_cvt_pk_bf16_f32 v87, v30, v31
	v_cvt_pk_bf16_f32 v86, v28, v29
	s_nop 3
	v_cvt_pk_bf16_f32 v81, v6, v7
	v_mfma_f32_16x16x32_bf16 v[12:15], v[76:79], v[68:71], v[12:15]
	v_cvt_pk_bf16_f32 v80, v4, v5
	v_cvt_pk_bf16_f32 v73, v10, v11
	v_cvt_pk_bf16_f32 v72, v8, v9
	ds_write2_b64 v198, v[82:83], v[80:81] offset0:32 offset1:36
	ds_write2_b64 v199, v[84:85], v[72:73] offset0:64 offset1:68
	s_nop 2
	v_cvt_pk_bf16_f32 v69, v14, v15
	v_cvt_pk_bf16_f32 v68, v12, v13
	ds_write2_b64 v200, v[86:87], v[68:69] offset0:96 offset1:100
	s_waitcnt vmcnt(0)
	s_cbranch_scc0 .LBB0_832
	v_mov_b64_e32 v[122:123], v[34:35]
	v_mov_b64_e32 v[106:107], v[42:43]
	v_mov_b64_e32 v[102:103], v[54:55]
	v_mov_b64_e32 v[90:91], v[58:59]
	v_mov_b64_e32 v[126:127], v[38:39]
	v_mov_b64_e32 v[110:111], v[46:47]
	v_mov_b64_e32 v[98:99], v[50:51]
	v_mov_b64_e32 v[94:95], v[62:63]
	v_mov_b64_e32 v[70:71], v[66:67]
	s_mov_b32 s4, s18
	v_mov_b64_e32 v[120:121], v[32:33]
	v_mov_b64_e32 v[104:105], v[40:41]
	v_mov_b64_e32 v[100:101], v[52:53]
	v_mov_b64_e32 v[88:89], v[56:57]
	v_mov_b64_e32 v[124:125], v[36:37]
	v_mov_b64_e32 v[108:109], v[44:45]
	v_mov_b64_e32 v[96:97], v[48:49]
	v_mov_b64_e32 v[92:93], v[60:61]
	v_mov_b64_e32 v[184:185], v[170:171]
	v_mov_b64_e32 v[182:183], v[172:173]
	v_mov_b64_e32 v[180:181], v[174:175]
	v_mov_b64_e32 v[178:179], v[176:177]
	v_mov_b64_e32 v[68:69], v[64:65]
	v_mov_b32_e32 v214, v159
	s_mov_b32 s18, s20
	s_branch .LBB0_812
